# v73 + P3 rebalance: GLU tiles on CUs 0-191 (2 units each), memory K/V GEMMs on CUs 192-255 followed by the remaining w_in_b transposes
# baseline (speedup 1.0000x reference)
.Ldf_skip_p3:
	s_add_u32 s20, s92, 0x11d00000
	s_addc_u32 s21, s93, 0
	s_add_u32 s18, s92, 0x17d00000
	s_addc_u32 s19, s93, 0
	v_mov_b32_e32 v16, v210
	s_waitcnt lgkmcnt(0)
	s_barrier
	s_cmpk_gt_i32 s2, 0xbf
	v_writelane_b32 v232, s78, 52
	v_readfirstlane_b32 s14, v16
	s_nop 0
	v_writelane_b32 v232, s79, 53
	s_cbranch_scc1 .LBB0_406
	v_lshlrev_b32_e32 v0, 4, v16
	v_add_u32_e32 v1, 0x2000, v0
	v_ashrrev_i32_e32 v2, 31, v1
	v_lshrrev_b32_e32 v2, 22, v2
	v_add_u32_e32 v2, v1, v2
	v_ashrrev_i32_e32 v8, 10, v2
	v_mul_i32_i24_e32 v2, 0x400, v8
	v_sub_u32_e32 v1, v1, v2
	v_lshrrev_b32_e32 v2, 4, v1
	v_bitop3_b32 v1, v2, v1, 32 bitop3:0x6c
	v_ashrrev_i32_e32 v2, 31, v1
	v_lshrrev_b32_e32 v2, 26, v2
	v_add_u32_e32 v2, v1, v2
	v_lshlrev_b32_e32 v3, 3, v8
	v_ashrrev_i32_e32 v9, 6, v2
	v_and_b32_e32 v3, -16, v3
	v_add_u32_e32 v3, v9, v3
	v_and_b32_e32 v4, 3, v9
	s_mov_b32 s0, 0x7fffe0
	v_lshrrev_b32_e32 v5, 2, v3
	v_lshlrev_b32_e32 v6, 1, v3
	v_and_b32_e32 v2, 0xc0, v2
	v_and_or_b32 v4, v3, s0, v4
	v_and_b32_e32 v5, 4, v5
	v_and_b32_e32 v6, 24, v6
	v_sub_u32_e32 v1, v1, v2
	v_mov_b32_e32 v2, 1
	v_or3_b32 v4, v4, v5, v6
	v_lshlrev_b32_e32 v5, 5, v8
	v_ashrrev_i16_sdwa v1, v2, sext(v1) dst_sel:DWORD dst_unused:UNUSED_PAD src0_sel:DWORD src1_sel:BYTE_0
	s_movk_i32 s15, 0x600
	v_and_b32_e32 v10, 32, v5
	v_bfe_i32 v11, v1, 0, 16
	v_mul_u32_u24_e32 v4, 0x600, v4
	v_add_u32_e32 v1, v10, v11
	v_mul_lo_u32 v3, v3, s15
	v_add_lshl_u32 v168, v4, v1, 1
	v_add_lshl_u32 v170, v1, v3, 1
	v_bfe_i32 v1, v16, 27, 1
	v_lshrrev_b32_e32 v1, 22, v1
	v_add_u32_e32 v1, v0, v1
	v_and_b32_e32 v1, 0xfffffc00, v1
	v_sub_u32_e32 v0, v0, v1
	v_lshrrev_b32_e32 v1, 4, v0
	v_bitop3_b32 v1, v1, v0, 32 bitop3:0x6c
	v_ashrrev_i32_e32 v0, 31, v0
	v_lshrrev_b32_e32 v0, 26, v0
	v_add_u32_e32 v0, v1, v0
	v_ashrrev_i32_e32 v12, 6, v0
	v_ashrrev_i32_e32 v0, 31, v16
	v_lshrrev_b32_e32 v0, 26, v0
	v_add_u32_e32 v0, v16, v0
	v_ashrrev_i32_e32 v13, 6, v0
	v_lshlrev_b32_e32 v0, 3, v13
	v_and_b32_e32 v0, -16, v0
	s_add_u32 s33, s92, 0x3000000
	v_add_u32_e32 v0, v12, v0
	v_and_b32_e32 v3, 3, v12
	s_addc_u32 s48, s93, 0
	v_and_or_b32 v3, v0, s0, v3
	s_lshr_b32 s0, s3, 29
	s_add_i32 s0, s2, s0
	s_ashr_i32 s22, s14, 6
	s_ashr_i32 s1, s0, 3
	s_and_b32 s0, s0, -8
	s_ashr_i32 s23, s14, 8
	s_lshl_b32 s49, s22, 10
	s_sub_i32 s0, s2, s0
	s_cmp_lt_i32 s0, 0
	s_cselect_b32 s4, 49, 48
	s_mul_i32 s0, s0, s4
	s_add_i32 s0, s0, s1
	s_mul_hi_i32 s1, s0, 0x2aaaaaab
	s_lshr_b32 s4, s1, 31
	s_ashr_i32 s1, s1, 2
	s_add_i32 s1, s1, s4
	s_lshl_b32 s4, s1, 2
	s_mul_i32 s1, s1, 24
	s_sub_i32 s0, s0, s1
	s_bfe_i32 s1, s0, 0x80000
	s_bfe_u32 s1, s1, 0x2000d
	v_lshrrev_b32_e32 v4, 2, v0
	v_lshlrev_b32_e32 v5, 1, v0
	s_add_i32 s1, s0, s1
	v_and_b32_e32 v4, 4, v4
	v_and_b32_e32 v5, 24, v5
	s_bfe_i32 s5, s1, 0x80000
	s_and_b32 s1, s1, 0xfc
	v_or3_b32 v3, v3, v4, v5
	v_lshlrev_b32_e32 v4, 5, v13
	s_sub_i32 s0, s0, s1
	v_and_b32_e32 v14, 32, v4
	v_mul_i32_i24_e32 v4, 64, v12
	s_sext_i32_i16 s5, s5
	s_sext_i32_i8 s0, s0
	v_sub_u32_e32 v1, v1, v4
	s_add_i32 s76, s4, s0
	s_ashr_i32 s0, s5, 2
	v_ashrrev_i16_sdwa v1, v2, sext(v1) dst_sel:DWORD dst_unused:UNUSED_PAD src0_sel:DWORD src1_sel:BYTE_0
	s_lshr_b32 s25, s5, 2
	s_mul_hi_i32 s1, s0, 0xc0000
	s_mul_i32 s0, s0, 0xc0000
	v_bfe_i32 v15, v1, 0, 16
	s_add_u32 s12, s33, s0
	v_mul_u32_u24_e32 v3, 0x600, v3
	v_add_u32_e32 v1, v14, v15
	s_addc_u32 s13, s48, s1
	s_add_i32 s50, s49, 0
	v_add_lshl_u32 v172, v3, v1, 1
	s_add_i32 m0, s50, 0x10000
	s_mul_i32 s4, s76, 0xc0000
	global_load_lds_dwordx4 v172, s[12:13]
	s_add_i32 m0, s50, 0x12000
	s_add_u32 s0, s12, 0x60000
	global_load_lds_dwordx4 v168, s[12:13]
	s_addc_u32 s1, s13, 0
	s_add_i32 m0, s50, 0x14000
	s_mul_hi_i32 s24, s76, 0xc0000
	global_load_lds_dwordx4 v172, s[0:1]
	s_add_i32 m0, s50, 0x16000
	s_add_u32 s4, s20, s4
	v_mul_lo_u32 v0, v0, s15
	s_addc_u32 s5, s21, s24
	s_add_i32 s51, s50, 0x2000
	v_add_lshl_u32 v174, v1, v0, 1
	global_load_lds_dwordx4 v168, s[0:1]
	s_mov_b32 m0, s50
	s_add_u32 s0, s4, 0x60000
	global_load_lds_dwordx4 v174, s[4:5]
	s_mov_b32 m0, s51
	s_addc_u32 s1, s5, 0
	s_add_i32 s52, s50, 0x4000
	global_load_lds_dwordx4 v170, s[4:5]
	s_mov_b32 m0, s52
	s_add_i32 s53, s50, 0x6000
	global_load_lds_dwordx4 v174, s[0:1]
	s_mov_b32 m0, s53
	v_mov_b32_e32 v173, 0
	global_load_lds_dwordx4 v170, s[0:1]
	v_mov_b32_e32 v169, v173
	v_mov_b32_e32 v175, v173
	v_mov_b32_e32 v171, v173
	s_cmp_eq_u32 s23, 1
	s_mov_b32 s62, 0
	v_lshl_add_u64 v[6:7], s[12:13], 0, v[172:173]
	v_lshl_add_u64 v[4:5], s[12:13], 0, v[168:169]
	v_lshl_add_u64 v[2:3], s[4:5], 0, v[174:175]
	v_lshl_add_u64 v[0:1], s[4:5], 0, v[170:171]
	s_cselect_b64 s[0:1], -1, 0
	s_cmp_lg_u32 s23, 1
	s_movk_i32 s24, 0x6000
	s_cbranch_scc1 .LBB0_389
	s_barrier

.LBB0_392:
	s_add_i32 s62, s62, 1
	s_mul_i32 s14, s62, 0xc0
	s_mov_b32 s15, 0
	s_add_u32 s14, s14, s2
	s_addc_u32 s15, s15, s3
	v_cmp_gt_i64_e32 vcc, s[14:15], v[182:183]
	v_cmp_lt_i64_e64 s[40:41], s[14:15], v[180:181]
	s_cbranch_vccnz .LBB0_394
	s_ashr_i32 s15, s14, 31
	s_lshr_b32 s15, s15, 29
	s_add_i32 s15, s14, s15
	s_ashr_i32 s24, s15, 3
	s_and_b32 s15, s15, -8
	s_sub_i32 s14, s14, s15
	s_cmp_lt_i32 s14, 0
	s_cselect_b32 s15, 49, 48
	s_mul_i32 s14, s14, s15
	s_add_i32 s14, s14, s24
	s_mul_hi_i32 s15, s14, 0x2aaaaaab
	s_lshr_b32 s24, s15, 31
	s_ashr_i32 s15, s15, 2
	s_add_i32 s15, s15, s24
	s_lshl_b32 s24, s15, 2
	s_sub_i32 s25, 64, s24
	s_min_i32 s25, s25, 4
	s_abs_i32 s26, s25
	v_cvt_f32_u32_e32 v0, s26
	s_sub_i32 s28, 0, s26
	s_mul_i32 s15, s15, 24
	s_sub_i32 s14, s14, s15
	v_rcp_iflag_f32_e32 v0, v0
	s_abs_i32 s15, s14
	s_xor_b32 s27, s14, s25
	s_ashr_i32 s27, s27, 31
	v_mul_f32_e32 v0, 0x4f7ffffe, v0
	v_cvt_u32_f32_e32 v0, v0
	s_nop 0
	v_readfirstlane_b32 s29, v0
	s_mul_i32 s28, s28, s29
	s_mul_hi_u32 s28, s29, s28
	s_add_i32 s29, s29, s28
	s_mul_hi_u32 s28, s15, s29
	s_mul_i32 s29, s28, s26
	s_sub_i32 s15, s15, s29
	s_add_i32 s38, s28, 1
	s_sub_i32 s29, s15, s26
	s_cmp_ge_u32 s15, s26
	s_cselect_b32 s28, s38, s28
	s_cselect_b32 s15, s29, s15
	s_add_i32 s29, s28, 1
	s_cmp_ge_u32 s15, s26
	s_cselect_b32 s15, s29, s28
	s_xor_b32 s15, s15, s27
	s_sub_i32 s68, s15, s27
	s_mul_i32 s15, s68, s25
	s_sub_i32 s14, s14, s15
	s_add_i32 s69, s24, s14

.LBB0_406:
	v_cvt_f32_u32_e32 v0, s94
	s_lshr_b32 s0, s94, 31
	s_add_i32 s0, s94, s0
	s_add_i32 s90, s94, s2
	v_rcp_iflag_f32_e32 v0, v0
	s_ashr_i32 s0, s0, 1
	s_movk_i32 s0, 0xc0
	s_sub_i32 s33, s90, s0
	s_add_u32 s0, s92, 0x10000
	v_mul_f32_e32 v0, 0x4f7ffffe, v0
	v_cvt_u32_f32_e32 v0, v0
	s_addc_u32 s1, s93, 0
	s_add_u32 s46, s92, 0x9500000
	s_addc_u32 s47, s93, 0
	s_sub_i32 s4, 0, s94
	v_readfirstlane_b32 s63, v0
	s_mul_i32 s4, s4, s63
	s_mul_hi_u32 s4, s63, s4
	s_add_i32 s63, s63, s4
	s_mul_hi_u32 s4, s33, s63
	s_mul_i32 s4, s4, s94
	s_sub_i32 s4, s33, s4
	s_sub_i32 s5, s4, s94
	s_cmp_ge_u32 s4, s94
	s_cselect_b32 s4, s5, s4
	s_sub_i32 s5, s4, s94
	s_cmp_ge_u32 s4, s94
	s_cselect_b32 s64, s5, s4
	v_mov_b32_e32 v14, v210
	s_cmp_gt_i32 s64, 31
	v_readfirstlane_b32 s24, v14
	s_cbranch_scc1 .LBB0_430
	s_ashr_i32 s65, s64, 31
	s_lshr_b32 s4, s65, 29
	s_add_i32 s14, s64, s4
	s_and_b32 s4, s14, -8
	s_sub_i32 s13, s64, s4
	s_cmp_gt_i32 s13, -1
	s_cbranch_scc0 .LBB0_409
	s_lshl_b32 s12, s13, 2
	s_ashr_i32 s4, s14, 3
	s_cbranch_execz .LBB0_410
	s_branch .LBB0_411
